# FoX diagonal tiles: a wave whose 32 queries all precede the tile skips its softmax and P.V work (tile tail staging and barrier kept)
# baseline (speedup 1.0000x reference)
.LBB0_794:
	v_mov_b32_e32 v208, s19
	ds_read_b32 v208, v208
	s_mul_i32 s8, s17, 0x4900
	s_add_i32 s20, s33, s8
	v_add_u32_e32 v0, s20, v173
	v_add_u32_e32 v0, v0, v156
	ds_read_b128 v[52:55], v0
	ds_read_b128 v[88:91], v0 offset:32
	ds_read_b128 v[92:95], v0 offset:4608
	ds_read_b128 v[96:99], v0 offset:4640
	ds_read_b128 v[100:103], v0 offset:64
	ds_read_b128 v[104:107], v0 offset:96
	ds_read_b128 v[108:111], v0 offset:4672
	ds_read_b128 v[112:115], v0 offset:4704
	s_waitcnt lgkmcnt(7)
	v_mfma_f32_32x32x16_bf16 v[68:83], v[52:55], v[116:119], v[4:19]
	s_waitcnt lgkmcnt(5)
	v_mfma_f32_32x32x16_bf16 v[52:67], v[92:95], v[116:119], v[4:19]
	v_mfma_f32_32x32x16_bf16 v[68:83], v[88:91], v[120:123], v[68:83]
	ds_read_b128 v[88:91], v0 offset:128
	ds_read_b128 v[92:95], v0 offset:4736
	s_waitcnt lgkmcnt(6)
	v_mfma_f32_32x32x16_bf16 v[52:67], v[96:99], v[120:123], v[52:67]
	s_waitcnt lgkmcnt(5)
	v_mfma_f32_32x32x16_bf16 v[68:83], v[100:103], v[124:127], v[68:83]
	s_waitcnt lgkmcnt(3)
	v_mfma_f32_32x32x16_bf16 v[52:67], v[108:111], v[124:127], v[52:67]
	v_mfma_f32_32x32x16_bf16 v[68:83], v[104:107], v[128:131], v[68:83]
	s_waitcnt lgkmcnt(2)
	v_mfma_f32_32x32x16_bf16 v[52:67], v[112:115], v[128:131], v[52:67]
	s_waitcnt lgkmcnt(1)
	v_mfma_f32_32x32x16_bf16 v[68:83], v[88:91], v[148:151], v[68:83]
	s_waitcnt lgkmcnt(0)
	v_mfma_f32_32x32x16_bf16 v[52:67], v[92:95], v[148:151], v[52:67]
	v_mov_b32_e32 v2, v208
	v_cmp_gt_i32_e32 vcc, s18, v2
	s_cbranch_vccnz .LBB0_796
	v_readfirstlane_b32 s34, v2
	v_readfirstlane_b32 s35, v154
	s_nop 1
	s_lshl_b32 s34, s34, 1
	s_lshr_b32 s35, s35, 5
	s_cmp_le_u32 s34, s35
	s_cbranch_scc1 .Lfm1_go
	v_mov_b32_e32 v84, 0
	v_mov_b32_e32 v85, 0
	s_add_i32 s8, s17, 1
	s_cmp_lg_u32 s8, 3
	s_cselect_b32 s22, s8, 0
	s_add_i32 s8, s22, 1
	s_cmp_lg_u32 s8, 3
	s_cselect_b32 s17, s8, 0
	s_branch .Lfox_sk1
.Lfm1_go:
	s_cmp_lt_u32 s34, s35
	s_cbranch_scc1 .Lfm1_d0
	s_cmp_eq_u32 s34, s35
	s_cbranch_scc1 .Lfm1_t0
	v_mov_b32_e32 v68, v185
	v_mov_b32_e32 v69, v185
	v_mov_b32_e32 v70, v185
	v_mov_b32_e32 v71, v185
	v_mov_b32_e32 v72, v185
	v_mov_b32_e32 v73, v185
	v_mov_b32_e32 v74, v185
	v_mov_b32_e32 v75, v185
	v_mov_b32_e32 v76, v185
	v_mov_b32_e32 v77, v185
	v_mov_b32_e32 v78, v185
	v_mov_b32_e32 v79, v185
	v_mov_b32_e32 v80, v185
	v_mov_b32_e32 v81, v185
	v_mov_b32_e32 v82, v185
	v_mov_b32_e32 v83, v185
	s_branch .Lfm1_d0

.Lfox_sk1:
	s_add_i32 s21, s13, -2
	s_cmp_ge_i32 s21, s12
	s_cbranch_scc1 .LBB0_802
	s_mul_i32 s8, s17, 0x4900
	s_add_i32 s10, s33, s8
	v_add3_u32 v0, s10, v171, v166
	s_waitcnt vmcnt(1)
	ds_write_b128 v0, v[132:135]
	s_waitcnt vmcnt(0)
	ds_write_b128 v0, v[136:139] offset:9216
	s_and_saveexec_b64 s[8:9], s[6:7]
	s_cbranch_execz .LBB0_801
	v_add_f32_e32 v170, v170, v223
	v_sub_f32_e32 v170, v155, v170
	v_cvt_pk_bf16_f32 v0, v170, 0
	v_and_b32_e32 v2, 0xffff, v0
	v_lshlrev_b32_e32 v0, 16, v0
	v_sub_f32_e32 v0, v170, v0
	v_cvt_pk_bf16_f32 v0, v0, 0
	v_lshl_or_b32 v0, v0, 16, v2
	v_mov_b32_e32 v2, v1
	v_mov_b32_e32 v3, v1
	v_add_u32_e32 v52, s10, v172
	ds_write_b128 v52, v[0:3] offset:128

.LBB0_807:
	v_mov_b32_e32 v208, s19
	ds_read_b32 v208, v208 offset:4
	s_mulk_i32 s22, 0x4900
	v_add_u32_e32 v0, s22, v174
	ds_read_b128 v[52:55], v0
	ds_read_b128 v[56:59], v0 offset:32
	ds_read_b128 v[60:63], v0 offset:4608
	ds_read_b128 v[64:67], v0 offset:4640
	ds_read_b128 v[68:71], v0 offset:64
	ds_read_b128 v[72:75], v0 offset:96
	ds_read_b128 v[76:79], v0 offset:4672
	ds_read_b128 v[80:83], v0 offset:4704
	s_waitcnt lgkmcnt(7)
	v_mfma_f32_32x32x16_bf16 v[100:115], v[52:55], v[116:119], v[4:19]
	s_waitcnt lgkmcnt(5)
	v_mfma_f32_32x32x16_bf16 v[84:99], v[60:63], v[116:119], v[4:19]
	v_mfma_f32_32x32x16_bf16 v[100:115], v[56:59], v[120:123], v[100:115]
	ds_read_b128 v[52:55], v0 offset:128
	ds_read_b128 v[56:59], v0 offset:4736
	s_waitcnt lgkmcnt(6)
	v_mfma_f32_32x32x16_bf16 v[84:99], v[64:67], v[120:123], v[84:99]
	s_waitcnt lgkmcnt(5)
	v_mfma_f32_32x32x16_bf16 v[100:115], v[68:71], v[124:127], v[100:115]
	s_waitcnt lgkmcnt(3)
	v_mfma_f32_32x32x16_bf16 v[84:99], v[76:79], v[124:127], v[84:99]
	v_mfma_f32_32x32x16_bf16 v[100:115], v[72:75], v[128:131], v[100:115]
	s_waitcnt lgkmcnt(2)
	v_mfma_f32_32x32x16_bf16 v[84:99], v[80:83], v[128:131], v[84:99]
	s_waitcnt lgkmcnt(1)
	v_mfma_f32_32x32x16_bf16 v[100:115], v[52:55], v[148:151], v[100:115]
	s_waitcnt lgkmcnt(0)
	v_mfma_f32_32x32x16_bf16 v[84:99], v[56:59], v[148:151], v[84:99]
	v_mov_b32_e32 v2, v208
	v_cmp_gt_i32_e32 vcc, s18, v2
	s_cbranch_vccnz .LBB0_809
	v_readfirstlane_b32 s34, v2
	v_readfirstlane_b32 s35, v154
	s_nop 1
	s_lshl_b32 s34, s34, 1
	s_lshr_b32 s35, s35, 5
	s_cmp_le_u32 s34, s35
	s_cbranch_scc1 .Lfm2_go
	v_mov_b32_e32 v84, 0
	v_mov_b32_e32 v85, 0
	v_mov_b32_e32 v176, v175
	s_branch .Lfox_sk2
.Lfm2_go:
	s_cmp_lt_u32 s34, s35
	s_cbranch_scc1 .Lfm2_d0
	s_cmp_eq_u32 s34, s35
	s_cbranch_scc1 .Lfm2_t0
	v_mov_b32_e32 v100, v185
	v_mov_b32_e32 v101, v185
	v_mov_b32_e32 v102, v185
	v_mov_b32_e32 v103, v185
	v_mov_b32_e32 v104, v185
	v_mov_b32_e32 v105, v185
	v_mov_b32_e32 v106, v185
	v_mov_b32_e32 v107, v185
	v_mov_b32_e32 v108, v185
	v_mov_b32_e32 v109, v185
	v_mov_b32_e32 v110, v185
	v_mov_b32_e32 v111, v185
	v_mov_b32_e32 v112, v185
	v_mov_b32_e32 v113, v185
	v_mov_b32_e32 v114, v185
	v_mov_b32_e32 v115, v185
	s_branch .Lfm2_d0

.Lfox_sk2:
	s_andn2_b64 vcc, exec, s[0:1]
	s_cbranch_vccnz .LBB0_788
	v_add3_u32 v0, s20, v171, v166
	s_waitcnt vmcnt(1)
	ds_write_b128 v0, v[140:143]
	s_waitcnt vmcnt(0)
	ds_write_b128 v0, v[144:147] offset:9216
	s_and_saveexec_b64 s[0:1], s[6:7]
	s_cbranch_execz .LBB0_787
	v_add_f32_e32 v167, v167, v222
	v_sub_f32_e32 v167, v155, v167
	v_cvt_pk_bf16_f32 v0, v167, 0
	v_and_b32_e32 v2, 0xffff, v0
	v_lshlrev_b32_e32 v0, 16, v0
	v_sub_f32_e32 v0, v167, v0
	v_cvt_pk_bf16_f32 v0, v0, 0
	v_lshl_or_b32 v0, v0, 16, v2
	v_mov_b32_e32 v2, v1
	v_mov_b32_e32 v3, v1
	v_add_u32_e32 v86, s20, v172
	ds_write_b128 v86, v[0:3] offset:128
	s_branch .LBB0_787
